# cross and pool item tops no longer drain the previous item's output stores (cross vmcnt(0) removed; pool vmcnt(0)->vmcnt(8), preheader drains once)
# baseline (speedup 1.0000x reference)
.LBB0_902:
	s_and_b32 s8, s14, 3
	s_mul_i32 s6, s0, 0x120000
	s_mul_hi_i32 s3, s0, 0x120000
	s_add_u32 s6, s92, s6
	s_addc_u32 s3, s93, s3
	s_lshl_b32 s15, s8, 7
	s_add_u32 s18, s6, s15
	s_addc_u32 s19, s3, 0
	s_ashr_i32 s3, s2, 31
	s_lshl_b64 s[6:7], s[2:3], 17
	s_add_u32 s3, s10, s6
	s_addc_u32 s7, s11, s7
	s_add_u32 s6, s3, s15
	s_addc_u32 s7, s7, 0
	s_lshl_b32 s2, s2, 2
	s_or_b32 s2, s2, s8
	s_ashr_i32 s3, s2, 31
	s_lshl_b64 s[2:3], s[2:3], 15
	s_add_u32 s8, s12, s2
	s_addc_u32 s9, s13, s3
	s_lshl_b64 s[0:1], s[0:1], 19
	s_add_u32 s0, s94, s0
	s_addc_u32 s1, s95, s1
	s_add_u32 s0, s0, s15
	v_mov_b32_e32 v34, v250
	s_addc_u32 s1, s1, 0
	s_add_u32 s2, s18, 0x1000
	v_ashrrev_i32_e32 v0, 1, v34
	v_bfe_u32 v58, v34, 5, 1
	s_nop 0
	v_bfi_b32 v98, s88, v0, v34
	v_mov_b64_e32 v[0:1], s[18:19]
	s_addc_u32 s3, s19, 0
	v_mad_i64_i32 v[0:1], s[18:19], v98, s33, v[0:1]
	v_lshlrev_b32_e32 v176, 4, v58
	v_lshl_add_u64 v[0:1], v[0:1], 0, v[176:177]
	global_load_dwordx4 v[94:97], v[0:1], off offset:3584
	global_load_dwordx4 v[90:93], v[0:1], off offset:3616
	global_load_dwordx4 v[86:89], v[0:1], off offset:3648
	global_load_dwordx4 v[82:85], v[0:1], off offset:3680
	v_ashrrev_i32_e32 v32, 3, v34
	v_lshlrev_b32_e32 v0, 4, v34
	v_and_b32_e32 v4, 0x70, v0
	v_mov_b32_e32 v5, v177
	v_ashrrev_i32_e32 v33, 31, v32
	v_xor_b32_e32 v37, v0, v34
	v_lshl_add_u64 v[0:1], s[6:7], 0, v[4:5]
	v_lshlrev_b64 v[2:3], 9, v[32:33]
	v_lshl_add_u64 v[24:25], v[0:1], 0, v[2:3]
	s_mov_b32 s6, 0x8000
	v_add_co_u32_e32 v8, vcc, s6, v24
	s_mov_b32 s6, 0x10000
	s_nop 0
	v_addc_co_u32_e32 v9, vcc, 0, v25, vcc
	v_lshl_add_u64 v[6:7], s[8:9], 0, v[2:3]
	v_add_co_u32_e32 v16, vcc, s6, v24
	v_lshl_add_u64 v[28:29], v[6:7], 0, v[4:5]
	s_nop 0
	v_addc_co_u32_e32 v17, vcc, 0, v25, vcc
	s_mov_b32 s6, 0x18000
	global_load_dwordx4 v[0:3], v[24:25], off
	global_load_dwordx4 v[4:7], v[28:29], off
	v_add_co_u32_e32 v24, vcc, s6, v24
	global_load_dwordx4 v[8:11], v[8:9], off
	s_nop 0
	global_load_dwordx4 v[12:15], v[28:29], off offset:128
	v_addc_co_u32_e32 v25, vcc, 0, v25, vcc
	global_load_dwordx4 v[16:19], v[16:17], off
	s_nop 0
	global_load_dwordx4 v[20:23], v[28:29], off offset:256
	s_nop 0
	global_load_dwordx4 v[24:27], v[24:25], off
	s_nop 0
	global_load_dwordx4 v[28:31], v[28:29], off offset:384
	v_lshlrev_b32_e32 v32, 7, v32
	s_movk_i32 s6, 0x70
	v_and_or_b32 v32, v37, s6, v32
	s_waitcnt lgkmcnt(0)
	s_barrier
	v_and_b32_e32 v35, 31, v34
	v_lshrrev_b32_e32 v36, 5, v34
	v_bfe_u32 v59, v34, 1, 3
	v_lshlrev_b32_e32 v60, 7, v35
	v_bitop3_b32 v36, v36, v59, 1 bitop3:0x6c
	v_lshl_or_b32 v163, v36, 4, v60
	v_ashrrev_i32_e32 v99, 31, v98
	s_add_i32 s14, s14, s90
	s_cmpk_gt_i32 s14, 0x2ff
	s_waitcnt vmcnt(7)
	ds_write_b128 v32, v[0:3]
	s_waitcnt vmcnt(6)
	ds_write_b128 v32, v[4:7] offset:8192
	s_waitcnt vmcnt(5)
	ds_write_b128 v32, v[8:11] offset:16384
	s_waitcnt vmcnt(4)
	ds_write_b128 v32, v[12:15] offset:24576
	s_waitcnt vmcnt(3)
	ds_write_b128 v32, v[16:19] offset:32768
	s_waitcnt vmcnt(2)
	ds_write_b128 v32, v[20:23] offset:40960
	s_waitcnt vmcnt(1)
	ds_write_b128 v32, v[24:27] offset:49152
	s_waitcnt vmcnt(0)
	ds_write_b128 v32, v[28:31] offset:57344
	v_mov_b64_e32 v[178:179], s[2:3]
	v_mad_i64_i32 v[178:179], s[2:3], v98, s33, v[178:179]
	v_lshl_add_u64 v[178:179], v[178:179], 0, v[176:177]
	v_lshlrev_b32_e32 v1, 1, v34
	v_lshrrev_b32_e32 v2, 1, v34
	v_and_b32_e32 v0, 19, v34
	v_and_b32_e32 v1, 8, v1
	v_and_b32_e32 v2, 4, v2
	v_or3_b32 v0, v1, v0, v2
	v_lshrrev_b32_e32 v37, 1, v0
	v_lshlrev_b32_e32 v38, 7, v0
	v_bitop3_b32 v0, v37, v58, 7 bitop3:0x6c
	v_lshl_or_b32 v103, v0, 4, v38
	s_waitcnt lgkmcnt(0)
	s_barrier
	ds_read_b128 v[0:3], v103
	ds_read_b128 v[16:19], v103 offset:4096
	v_or_b32_e32 v32, 2, v58
	v_bitop3_b32 v32, v37, v32, 7 bitop3:0x6c
	v_lshl_or_b32 v105, v32, 4, v38
	ds_read_b128 v[32:35], v105
	s_waitcnt lgkmcnt(2)
	v_mfma_f32_32x32x16_bf16 v[0:15], v[0:3], v[94:97], 0
	ds_read_b128 v[150:153], v163 offset:12288
	s_mov_b32 s2, 0xf149f2ca
	s_waitcnt lgkmcnt(1)
	v_mfma_f32_32x32x16_bf16 v[0:15], v[32:35], v[90:93], v[0:15]
	ds_read_b128 v[32:35], v105 offset:4096
	v_mfma_f32_32x32x16_bf16 v[16:31], v[16:19], v[94:97], 0
	s_waitcnt lgkmcnt(0)
	v_mfma_f32_32x32x16_bf16 v[16:31], v[32:35], v[90:93], v[16:31]
	v_or_b32_e32 v32, 4, v58
	v_bitop3_b32 v32, v37, v32, 7 bitop3:0x6c
	v_lshl_or_b32 v107, v32, 4, v38
	ds_read_b128 v[32:35], v107
	s_waitcnt lgkmcnt(0)
	v_mfma_f32_32x32x16_bf16 v[0:15], v[32:35], v[86:89], v[0:15]
	ds_read_b128 v[32:35], v107 offset:4096
	s_waitcnt lgkmcnt(0)
	v_mfma_f32_32x32x16_bf16 v[16:31], v[32:35], v[86:89], v[16:31]
	global_load_dwordx4 v[78:81], v[178:179], off
	v_or_b32_e32 v32, 6, v58
	v_bitop3_b32 v32, v37, v32, 7 bitop3:0x6c
	v_lshl_or_b32 v101, v32, 4, v38
	ds_read_b128 v[32:35], v101
	s_waitcnt lgkmcnt(0)
	v_mfma_f32_32x32x16_bf16 v[0:15], v[32:35], v[82:85], v[0:15]
	ds_read_b128 v[32:35], v101 offset:4096
	s_waitcnt lgkmcnt(0)
	v_mfma_f32_32x32x16_bf16 v[16:31], v[32:35], v[82:85], v[16:31]
	s_nop 8
	v_max_f32_e32 v32, v1, v1
	v_max_f32_e32 v33, v0, v0
	v_max_f32_e32 v32, v33, v32
	v_max3_f32 v32, v32, v2, v3
	v_max3_f32 v32, v32, v4, v5
	v_max3_f32 v32, v32, v6, v7
	v_max3_f32 v32, v32, v8, v9
	v_max3_f32 v32, v32, v10, v11
	v_max3_f32 v32, v32, v12, v13
	v_max3_f32 v32, v32, v14, v15
	v_max3_f32 v32, v32, v16, v17
	v_max3_f32 v32, v32, v18, v19
	v_max3_f32 v32, v32, v20, v21
	v_max3_f32 v32, v32, v22, v23
	v_max3_f32 v32, v32, v24, v25
	v_max3_f32 v32, v32, v26, v27
	v_max3_f32 v32, v32, v28, v29
	v_max3_f32 v32, v32, v30, v31
	v_mov_b32_e32 v33, v32
	s_nop 1
	v_permlane32_swap_b32_e32 v32, v33
	v_max3_f32 v109, v32, v33, s2
	v_sub_f32_e32 v0, v0, v109
	v_exp_f32_e32 v38, v0
	v_sub_f32_e32 v0, v16, v109
	v_exp_f32_e32 v39, v0
	v_sub_f32_e32 v37, 0xf149f2ca, v109
	v_add_f32_e32 v0, v38, v39
	v_add_f32_e32 v33, 0, v0
	v_sub_f32_e32 v0, v1, v109
	v_exp_f32_e32 v40, v0
	v_sub_f32_e32 v0, v17, v109
	v_exp_f32_e32 v41, v0
	v_sub_f32_e32 v0, v2, v109
	v_exp_f32_e32 v16, v0
	v_sub_f32_e32 v0, v18, v109
	v_exp_f32_e32 v32, v0
	v_add_f32_e32 v17, v40, v41
	v_cvt_pk_bf16_f32 v62, v38, v40
	v_cvt_pk_bf16_f32 v54, v39, v41
	v_add_f32_e32 v0, v16, v32
	v_add_f32_e32 v1, v17, v33
	s_nop 0
	v_add_f32_e32 v34, v0, v0
	v_add_f32_e32 v35, v0, v1
	v_sub_f32_e32 v0, v3, v109
	v_exp_f32_e32 v17, v0
	v_sub_f32_e32 v0, v19, v109
	v_exp_f32_e32 v33, v0
	v_sub_f32_e32 v0, v4, v109
	v_exp_f32_e32 v18, v0
	v_sub_f32_e32 v0, v20, v109
	v_exp_f32_e32 v34, v0
	v_add_f32_e32 v19, v17, v33
	v_cvt_pk_bf16_f32 v63, v16, v17
	v_cvt_pk_bf16_f32 v55, v32, v33
	v_add_f32_e32 v0, v18, v34
	v_add_f32_e32 v1, v19, v35
	s_nop 0
	v_add_f32_e32 v144, v0, v1
	v_add_f32_e32 v145, v1, v0
	v_sub_f32_e32 v0, v5, v109
	v_exp_f32_e32 v104, v0
	v_sub_f32_e32 v0, v21, v109
	v_exp_f32_e32 v100, v0
	v_sub_f32_e32 v0, v6, v109
	v_exp_f32_e32 v108, v0
	v_sub_f32_e32 v0, v22, v109
	v_exp_f32_e32 v102, v0
	v_sub_f32_e32 v0, v7, v109
	v_exp_f32_e32 v112, v0
	v_sub_f32_e32 v0, v23, v109
	v_exp_f32_e32 v106, v0
	v_sub_f32_e32 v0, v8, v109
	v_exp_f32_e32 v116, v0
	v_sub_f32_e32 v0, v24, v109
	v_exp_f32_e32 v110, v0
	v_sub_f32_e32 v0, v9, v109
	v_exp_f32_e32 v120, v0
	v_sub_f32_e32 v0, v25, v109
	v_exp_f32_e32 v114, v0
	v_sub_f32_e32 v0, v10, v109
	v_exp_f32_e32 v122, v0
	v_sub_f32_e32 v0, v26, v109
	v_exp_f32_e32 v118, v0
	v_sub_f32_e32 v0, v11, v109
	v_exp_f32_e32 v128, v0
	v_sub_f32_e32 v0, v27, v109
	v_exp_f32_e32 v124, v0
	v_sub_f32_e32 v0, v12, v109
	v_exp_f32_e32 v132, v0
	v_sub_f32_e32 v0, v28, v109
	v_exp_f32_e32 v126, v0
	v_sub_f32_e32 v0, v13, v109
	v_exp_f32_e32 v136, v0
	v_sub_f32_e32 v0, v29, v109
	v_exp_f32_e32 v130, v0
	v_sub_f32_e32 v0, v14, v109
	v_exp_f32_e32 v140, v0
	v_sub_f32_e32 v0, v30, v109
	v_exp_f32_e32 v134, v0
	v_sub_f32_e32 v0, v15, v109
	v_exp_f32_e32 v142, v0
	v_sub_f32_e32 v0, v31, v109
	v_exp_f32_e32 v138, v0
	v_exp_f32_e32 v0, v37
	v_cvt_pk_bf16_f32 v56, v34, v100
	ds_read_b128 v[34:37], v163 offset:8192
	v_cvt_pk_bf16_f32 v64, v18, v104
	v_mul_f32_e32 v0, 0, v0
	v_mov_b32_e32 v1, v0
	v_mov_b32_e32 v2, v0
	v_mov_b32_e32 v3, v0
	v_mov_b32_e32 v4, v0
	v_mov_b32_e32 v5, v0
	v_mov_b32_e32 v6, v0
	v_mov_b32_e32 v7, v0
	v_mov_b32_e32 v8, v0
	v_mov_b32_e32 v9, v0
	v_mov_b32_e32 v10, v0
	v_mov_b32_e32 v11, v0
	v_mov_b32_e32 v12, v0
	v_mov_b32_e32 v13, v0
	v_mov_b32_e32 v14, v0
	v_mov_b32_e32 v15, v0
	v_cvt_pk_bf16_f32 v65, v108, v112
	v_cvt_pk_bf16_f32 v146, v116, v120
	v_cvt_pk_bf16_f32 v147, v122, v128
	s_waitcnt lgkmcnt(0)
	v_mfma_f32_32x32x16_bf16 v[18:33], v[34:37], v[62:65], v[0:15]
	v_mov_b64_e32 v[48:49], v[14:15]
	v_mov_b64_e32 v[46:47], v[12:13]
	v_mov_b64_e32 v[44:45], v[10:11]
	v_mov_b64_e32 v[42:43], v[8:9]
	v_mov_b64_e32 v[40:41], v[6:7]
	v_mov_b64_e32 v[38:39], v[4:5]
	v_mov_b64_e32 v[36:37], v[2:3]
	v_mov_b64_e32 v[34:35], v[0:1]
	v_bitop3_b32 v1, v58, v59, 2 bitop3:0x36
	v_lshl_or_b32 v162, v1, 4, v60
	ds_read_b128 v[2:5], v162 offset:8192
	v_cvt_pk_bf16_f32 v148, v132, v136
	v_cvt_pk_bf16_f32 v149, v140, v142
	v_mfma_f32_32x32x16_bf16 v[34:49], v[150:153], v[62:65], v[34:49]
	v_bitop3_b32 v1, v58, v59, 4 bitop3:0x36
	v_lshl_or_b32 v161, v1, 4, v60
	v_cvt_pk_bf16_f32 v57, v102, v106
	v_bitop3_b32 v1, v58, v59, 6 bitop3:0x36
	v_lshl_or_b32 v160, v1, 4, v60
	v_cvt_pk_bf16_f32 v50, v110, v114
	v_cvt_pk_bf16_f32 v51, v118, v124
	s_waitcnt lgkmcnt(0)
	v_mfma_f32_32x32x16_bf16 v[18:33], v[2:5], v[146:149], v[18:33]
	ds_read_b128 v[2:5], v162 offset:12288
	v_cvt_pk_bf16_f32 v52, v126, v130
	v_cvt_pk_bf16_f32 v53, v134, v138
	v_mov_b32_e32 v145, v177
	s_waitcnt lgkmcnt(0)
	v_mfma_f32_32x32x16_bf16 v[34:49], v[2:5], v[146:149], v[34:49]
	ds_read_b128 v[2:5], v161 offset:8192
	ds_read_b128 v[146:149], v105 offset:16384
	s_waitcnt lgkmcnt(1)
	v_mfma_f32_32x32x16_bf16 v[18:33], v[2:5], v[54:57], v[18:33]
	ds_read_b128 v[2:5], v161 offset:12288
	s_waitcnt lgkmcnt(0)
	v_mfma_f32_32x32x16_bf16 v[34:49], v[2:5], v[54:57], v[34:49]
	ds_read_b128 v[2:5], v160 offset:8192
	s_waitcnt lgkmcnt(0)
	v_mfma_f32_32x32x16_bf16 v[18:33], v[2:5], v[50:53], v[18:33]
	ds_read_b128 v[2:5], v160 offset:12288
	s_waitcnt lgkmcnt(0)
	v_mfma_f32_32x32x16_bf16 v[34:49], v[2:5], v[50:53], v[34:49]
	global_load_dwordx4 v[74:77], v[178:179], off offset:32
	ds_read_b128 v[2:5], v103 offset:16384
	ds_read_b128 v[50:53], v103 offset:20480
	s_waitcnt lgkmcnt(1)
	v_mfma_f32_32x32x16_bf16 v[2:17], v[2:5], v[94:97], 0
	v_mfma_f32_32x32x16_bf16 v[2:17], v[146:149], v[90:93], v[2:17]
	ds_read_b128 v[146:149], v105 offset:20480
	s_waitcnt lgkmcnt(1)
	v_mfma_f32_32x32x16_bf16 v[50:65], v[50:53], v[94:97], 0
	s_waitcnt lgkmcnt(0)
	v_mfma_f32_32x32x16_bf16 v[50:65], v[146:149], v[90:93], v[50:65]
	ds_read_b128 v[146:149], v107 offset:16384
	s_waitcnt lgkmcnt(0)
	v_mfma_f32_32x32x16_bf16 v[2:17], v[146:149], v[86:89], v[2:17]
	ds_read_b128 v[146:149], v107 offset:20480
	s_waitcnt lgkmcnt(0)
	v_mfma_f32_32x32x16_bf16 v[50:65], v[146:149], v[86:89], v[50:65]
	ds_read_b128 v[146:149], v101 offset:16384
	s_waitcnt lgkmcnt(0)
	v_mfma_f32_32x32x16_bf16 v[2:17], v[146:149], v[82:85], v[2:17]
	ds_read_b128 v[146:149], v101 offset:20480
	s_waitcnt lgkmcnt(0)
	v_mfma_f32_32x32x16_bf16 v[50:65], v[146:149], v[82:85], v[50:65]
	s_nop 8
	v_max_f32_e32 v1, v3, v3
	v_max_f32_e32 v111, v2, v2
	v_max_f32_e32 v1, v111, v1
	v_max3_f32 v1, v1, v4, v5
	v_max3_f32 v1, v1, v6, v7
	v_max3_f32 v1, v1, v8, v9
	v_max3_f32 v1, v1, v10, v11
	v_max3_f32 v1, v1, v12, v13
	v_max3_f32 v1, v1, v14, v15
	v_max3_f32 v1, v1, v16, v17
	v_max3_f32 v1, v1, v50, v51
	v_max3_f32 v1, v1, v52, v53
	v_max3_f32 v1, v1, v54, v55
	v_max3_f32 v1, v1, v56, v57
	v_max3_f32 v1, v1, v58, v59
	v_max3_f32 v1, v1, v60, v61
	v_max3_f32 v1, v1, v62, v63
	v_max3_f32 v1, v1, v64, v65
	v_mov_b32_e32 v111, v1
	s_nop 1
	v_permlane32_swap_b32_e32 v1, v111
	v_max3_f32 v1, v109, v1, v111
	v_sub_f32_e32 v2, v2, v1
	v_exp_f32_e32 v111, v2
	v_sub_f32_e32 v2, v50, v1
	v_exp_f32_e32 v113, v2
	v_sub_f32_e32 v109, v109, v1
	v_exp_f32_e32 v150, v109
	v_add_f32_e32 v2, v111, v113
	v_add_f32_e32 v153, 0, v2
	v_sub_f32_e32 v2, v3, v1
	v_exp_f32_e32 v115, v2
	v_sub_f32_e32 v2, v51, v1
	v_exp_f32_e32 v117, v2
	v_sub_f32_e32 v2, v4, v1
	v_exp_f32_e32 v50, v2
	v_sub_f32_e32 v2, v52, v1
	v_exp_f32_e32 v152, v2
	v_add_f32_e32 v51, v115, v117
	v_add_f32_e32 v2, v50, v152
	v_add_f32_e32 v3, v51, v153
	s_nop 0
	v_add_f32_e32 v154, v2, v2
	v_add_f32_e32 v155, v2, v3
	v_sub_f32_e32 v2, v5, v1
	v_exp_f32_e32 v51, v2
	v_sub_f32_e32 v2, v53, v1
	v_exp_f32_e32 v119, v2
	v_sub_f32_e32 v2, v6, v1
	v_exp_f32_e32 v52, v2
	v_sub_f32_e32 v2, v54, v1
	v_exp_f32_e32 v154, v2
	v_add_f32_e32 v53, v51, v119
	v_mul_f32_e32 v4, v20, v150
	v_mul_f32_e32 v5, v21, v150
	v_mul_f32_e32 v20, v36, v150
	v_mul_f32_e32 v21, v37, v150
	v_add_f32_e32 v2, v52, v154
	v_add_f32_e32 v3, v53, v155
	s_nop 0
	v_add_f32_e32 v156, v2, v2
	v_add_f32_e32 v157, v2, v3
	v_sub_f32_e32 v2, v7, v1
	v_exp_f32_e32 v53, v2
	v_sub_f32_e32 v2, v55, v1
	v_exp_f32_e32 v121, v2
	v_sub_f32_e32 v2, v8, v1
	v_exp_f32_e32 v54, v2
	v_sub_f32_e32 v2, v56, v1
	v_exp_f32_e32 v156, v2
	v_add_f32_e32 v55, v53, v121
	v_mul_f32_e32 v6, v22, v150
	v_mul_f32_e32 v7, v23, v150
	v_mul_f32_e32 v22, v38, v150
	v_mul_f32_e32 v23, v39, v150
	v_add_f32_e32 v2, v54, v156
	v_add_f32_e32 v3, v55, v157
	v_cvt_pk_bf16_f32 v38, v113, v117
	v_add_f32_e32 v158, v2, v2
	v_add_f32_e32 v159, v2, v3
	v_sub_f32_e32 v2, v9, v1
	v_exp_f32_e32 v55, v2
	v_sub_f32_e32 v2, v57, v1
	v_exp_f32_e32 v123, v2
	v_sub_f32_e32 v2, v10, v1
	v_exp_f32_e32 v56, v2
	v_sub_f32_e32 v2, v58, v1
	v_exp_f32_e32 v158, v2
	v_add_f32_e32 v57, v55, v123
	v_mul_f32_e32 v8, v24, v150
	v_mul_f32_e32 v9, v25, v150
	v_mul_f32_e32 v24, v40, v150
	v_mul_f32_e32 v25, v41, v150
	v_add_f32_e32 v2, v56, v158
	v_add_f32_e32 v3, v57, v159
	v_cvt_pk_bf16_f32 v39, v152, v119
	v_add_f32_e32 v164, v2, v2
	v_add_f32_e32 v165, v2, v3
	v_sub_f32_e32 v2, v11, v1
	v_exp_f32_e32 v57, v2
	v_sub_f32_e32 v2, v59, v1
	v_exp_f32_e32 v125, v2
	v_sub_f32_e32 v2, v12, v1
	v_exp_f32_e32 v58, v2
	v_sub_f32_e32 v2, v60, v1
	v_exp_f32_e32 v164, v2
	v_add_f32_e32 v59, v57, v125
	v_mul_f32_e32 v10, v26, v150
	v_mul_f32_e32 v11, v27, v150
	v_mul_f32_e32 v26, v42, v150
	v_mul_f32_e32 v27, v43, v150
	v_add_f32_e32 v2, v58, v164
	v_add_f32_e32 v3, v59, v165
	v_cvt_pk_bf16_f32 v42, v56, v57
	v_add_f32_e32 v166, v2, v2
	v_add_f32_e32 v167, v2, v3
	v_sub_f32_e32 v2, v13, v1
	v_exp_f32_e32 v59, v2
	v_sub_f32_e32 v2, v61, v1
	v_exp_f32_e32 v127, v2
	v_sub_f32_e32 v2, v14, v1
	v_exp_f32_e32 v60, v2
	v_sub_f32_e32 v2, v62, v1
	v_exp_f32_e32 v166, v2
	v_add_f32_e32 v61, v59, v127
	v_mul_f32_e32 v12, v28, v150
	v_mul_f32_e32 v13, v29, v150
	v_mul_f32_e32 v28, v44, v150
	v_mul_f32_e32 v29, v45, v150
	v_add_f32_e32 v2, v60, v166
	v_add_f32_e32 v3, v61, v167
	v_cvt_pk_bf16_f32 v43, v58, v59
	v_add_f32_e32 v168, v2, v2
	v_add_f32_e32 v169, v2, v3
	v_sub_f32_e32 v2, v15, v1
	v_exp_f32_e32 v61, v2
	v_sub_f32_e32 v2, v63, v1
	v_exp_f32_e32 v129, v2
	v_sub_f32_e32 v2, v16, v1
	v_exp_f32_e32 v62, v2
	v_sub_f32_e32 v2, v64, v1
	v_exp_f32_e32 v168, v2
	v_sub_f32_e32 v2, v17, v1
	v_mul_f32_e32 v16, v32, v150
	v_mul_f32_e32 v17, v33, v150
	v_mul_f32_e32 v14, v30, v150
	v_mul_f32_e32 v15, v31, v150
	v_mul_f32_e32 v32, v48, v150
	v_mul_f32_e32 v33, v49, v150
	v_mul_f32_e32 v30, v46, v150
	v_mul_f32_e32 v31, v47, v150
	v_cvt_pk_bf16_f32 v47, v50, v51
	v_cvt_pk_bf16_f32 v48, v52, v53
	ds_read_b128 v[50:53], v163 offset:24576
	v_add_f32_e32 v63, v61, v129
	v_add_f32_e32 v148, v62, v168
	v_add_f32_e32 v149, v63, v169
	v_exp_f32_e32 v63, v2
	v_sub_f32_e32 v2, v65, v1
	v_exp_f32_e32 v64, v2
	v_mul_f32_e32 v2, v18, v150
	v_mul_f32_e32 v3, v19, v150
	v_cvt_pk_bf16_f32 v46, v111, v115
	v_cvt_pk_bf16_f32 v49, v54, v55
	v_mul_f32_e32 v18, v34, v150
	v_mul_f32_e32 v19, v35, v150
	v_cvt_pk_bf16_f32 v44, v60, v61
	s_waitcnt lgkmcnt(0)
	v_mfma_f32_32x32x16_bf16 v[2:17], v[50:53], v[46:49], v[2:17]
	ds_read_b128 v[50:53], v163 offset:28672
	v_cvt_pk_bf16_f32 v45, v62, v63
	v_cvt_pk_bf16_f32 v40, v154, v121
	v_cvt_pk_bf16_f32 v41, v156, v123
	v_cvt_pk_bf16_f32 v34, v158, v125
	v_cvt_pk_bf16_f32 v35, v164, v127
	v_cvt_pk_bf16_f32 v36, v166, v129
	s_waitcnt lgkmcnt(0)
	v_mfma_f32_32x32x16_bf16 v[18:33], v[50:53], v[46:49], v[18:33]
	global_load_dwordx4 v[70:73], v[178:179], off offset:64
	ds_read_b128 v[46:49], v162 offset:24576
	v_cvt_pk_bf16_f32 v37, v168, v64
	ds_read_b128 v[152:155], v105 offset:32768
	ds_read_b128 v[50:53], v103 offset:36864
	v_add_f32_e32 v146, v63, v64
	s_waitcnt lgkmcnt(2)
	v_mfma_f32_32x32x16_bf16 v[2:17], v[46:49], v[42:45], v[2:17]
	ds_read_b128 v[46:49], v162 offset:28672
	s_waitcnt lgkmcnt(0)
	v_mfma_f32_32x32x16_bf16 v[18:33], v[46:49], v[42:45], v[18:33]
	ds_read_b128 v[42:45], v161 offset:24576
	s_waitcnt lgkmcnt(0)
	v_mfma_f32_32x32x16_bf16 v[2:17], v[42:45], v[38:41], v[2:17]
	ds_read_b128 v[42:45], v161 offset:28672
	s_waitcnt lgkmcnt(0)
	v_mfma_f32_32x32x16_bf16 v[18:33], v[42:45], v[38:41], v[18:33]
	ds_read_b128 v[38:41], v160 offset:24576
	s_waitcnt lgkmcnt(0)
	v_mfma_f32_32x32x16_bf16 v[2:17], v[38:41], v[34:37], v[2:17]
	ds_read_b128 v[38:41], v160 offset:28672
	s_waitcnt lgkmcnt(0)
	v_mfma_f32_32x32x16_bf16 v[18:33], v[38:41], v[34:37], v[18:33]
	ds_read_b128 v[34:37], v103 offset:32768
	s_waitcnt lgkmcnt(0)
	v_mfma_f32_32x32x16_bf16 v[34:49], v[34:37], v[94:97], 0
	v_mfma_f32_32x32x16_bf16 v[34:49], v[152:155], v[90:93], v[34:49]
	ds_read_b128 v[152:155], v105 offset:36864
	v_mfma_f32_32x32x16_bf16 v[50:65], v[50:53], v[94:97], 0
	s_waitcnt lgkmcnt(0)
	v_mfma_f32_32x32x16_bf16 v[50:65], v[152:155], v[90:93], v[50:65]
	global_load_dwordx4 v[66:69], v[178:179], off offset:96
	ds_read_b128 v[152:155], v107 offset:32768
	s_waitcnt lgkmcnt(0)
	v_mfma_f32_32x32x16_bf16 v[34:49], v[152:155], v[86:89], v[34:49]
	ds_read_b128 v[152:155], v107 offset:36864
	s_waitcnt lgkmcnt(0)
	v_mfma_f32_32x32x16_bf16 v[50:65], v[152:155], v[86:89], v[50:65]
	ds_read_b128 v[152:155], v101 offset:32768
	s_waitcnt lgkmcnt(0)
	v_mfma_f32_32x32x16_bf16 v[34:49], v[152:155], v[82:85], v[34:49]
	ds_read_b128 v[152:155], v101 offset:36864
	s_waitcnt lgkmcnt(0)
	v_mfma_f32_32x32x16_bf16 v[50:65], v[152:155], v[82:85], v[50:65]
	s_nop 8
	v_max_f32_e32 v109, v35, v35
	v_max_f32_e32 v111, v34, v34
	v_max_f32_e32 v109, v111, v109
	v_max3_f32 v109, v109, v36, v37
	v_max3_f32 v109, v109, v38, v39
	v_max3_f32 v109, v109, v40, v41
	v_max3_f32 v109, v109, v42, v43
	v_max3_f32 v109, v109, v44, v45
	v_max3_f32 v109, v109, v46, v47
	v_max3_f32 v109, v109, v48, v49
	v_max3_f32 v109, v109, v50, v51
	v_max3_f32 v109, v109, v52, v53
	v_max3_f32 v109, v109, v54, v55
	v_max3_f32 v109, v109, v56, v57
	v_max3_f32 v109, v109, v58, v59
	v_max3_f32 v109, v109, v60, v61
	v_max3_f32 v109, v109, v62, v63
	v_max3_f32 v109, v109, v64, v65
	v_mov_b32_e32 v111, v109
	s_nop 1
	v_permlane32_swap_b32_e32 v109, v111
	v_max3_f32 v109, v1, v109, v111
	v_sub_f32_e32 v34, v34, v109
	v_exp_f32_e32 v111, v34
	v_sub_f32_e32 v34, v50, v109
	v_exp_f32_e32 v113, v34
	v_sub_f32_e32 v1, v1, v109
	v_exp_f32_e32 v156, v1
	v_add_f32_e32 v34, v111, v113
	v_add_f32_e32 v159, 0, v34
	v_sub_f32_e32 v34, v35, v109
	v_exp_f32_e32 v115, v34
	v_sub_f32_e32 v34, v51, v109
	v_exp_f32_e32 v117, v34
	v_sub_f32_e32 v34, v36, v109
	v_sub_f32_e32 v36, v52, v109
	v_exp_f32_e32 v34, v34
	v_exp_f32_e32 v158, v36
	v_add_f32_e32 v35, v115, v117
	v_sub_f32_e32 v36, v53, v109
	v_exp_f32_e32 v119, v36
	v_add_f32_e32 v50, v34, v158
	v_add_f32_e32 v51, v35, v159
	v_sub_f32_e32 v35, v37, v109
	v_add_f32_e32 v51, v50, v51
	v_add_f32_e32 v50, v50, v50
	v_exp_f32_e32 v35, v35
	v_sub_f32_e32 v36, v38, v109
	v_sub_f32_e32 v38, v54, v109
	v_exp_f32_e32 v36, v36
	v_exp_f32_e32 v50, v38
	v_add_f32_e32 v37, v35, v119
	v_sub_f32_e32 v38, v55, v109
	v_mul_f32_e32 v16, v16, v156
	v_mul_f32_e32 v17, v17, v156
	v_add_f32_e32 v52, v36, v50
	v_add_f32_e32 v53, v37, v51
	v_sub_f32_e32 v37, v39, v109
	v_add_f32_e32 v53, v52, v53
	v_add_f32_e32 v52, v52, v52
	v_exp_f32_e32 v37, v37
	v_exp_f32_e32 v51, v38
	v_sub_f32_e32 v38, v40, v109
	v_sub_f32_e32 v40, v56, v109
	v_exp_f32_e32 v38, v38
	v_exp_f32_e32 v52, v40
	v_add_f32_e32 v39, v37, v51
	v_sub_f32_e32 v40, v57, v109
	v_mul_f32_e32 v14, v14, v156
	v_mul_f32_e32 v15, v15, v156
	v_add_f32_e32 v54, v38, v52
	v_add_f32_e32 v55, v39, v53
	v_sub_f32_e32 v39, v41, v109
	v_add_f32_e32 v55, v54, v55
	v_add_f32_e32 v54, v54, v54
	v_exp_f32_e32 v39, v39
	v_exp_f32_e32 v53, v40
	v_sub_f32_e32 v40, v42, v109
	v_sub_f32_e32 v42, v58, v109
	v_exp_f32_e32 v40, v40
	v_exp_f32_e32 v54, v42
	v_add_f32_e32 v41, v39, v53
	v_sub_f32_e32 v42, v59, v109
	v_mul_f32_e32 v12, v12, v156
	v_mul_f32_e32 v13, v13, v156
	v_add_f32_e32 v56, v40, v54
	v_add_f32_e32 v57, v41, v55
	v_sub_f32_e32 v41, v43, v109
	v_exp_f32_e32 v55, v42
	v_sub_f32_e32 v42, v44, v109
	v_add_f32_e32 v57, v56, v57
	v_add_f32_e32 v56, v56, v56
	v_exp_f32_e32 v41, v41
	v_exp_f32_e32 v58, v42
	v_sub_f32_e32 v42, v60, v109
	v_exp_f32_e32 v56, v42
	v_add_f32_e32 v59, v41, v55
	v_mul_f32_e32 v10, v10, v156
	v_mul_f32_e32 v11, v11, v156
	v_mul_f32_e32 v8, v8, v156
	v_mul_f32_e32 v9, v9, v156
	v_add_f32_e32 v42, v58, v56
	v_add_f32_e32 v43, v59, v57
	v_mul_f32_e32 v6, v6, v156
	v_mul_f32_e32 v7, v7, v156
	v_add_f32_e32 v164, v42, v42
	v_add_f32_e32 v165, v42, v43
	v_sub_f32_e32 v42, v45, v109
	v_exp_f32_e32 v57, v42
	v_sub_f32_e32 v42, v61, v109
	v_exp_f32_e32 v59, v42
	v_sub_f32_e32 v42, v46, v109
	v_exp_f32_e32 v44, v42
	v_sub_f32_e32 v42, v62, v109
	v_exp_f32_e32 v164, v42
	v_add_f32_e32 v45, v57, v59
	v_mul_f32_e32 v4, v4, v156
	v_mul_f32_e32 v5, v5, v156
	v_mul_f32_e32 v2, v2, v156
	v_mul_f32_e32 v3, v3, v156
	v_add_f32_e32 v42, v44, v164
	v_add_f32_e32 v43, v45, v165
	v_cvt_pk_bf16_f32 v46, v111, v115
	v_add_f32_e32 v60, v42, v42
	v_add_f32_e32 v61, v42, v43
	v_sub_f32_e32 v42, v47, v109
	v_exp_f32_e32 v45, v42
	v_sub_f32_e32 v42, v63, v109
	v_exp_f32_e32 v121, v42
	v_sub_f32_e32 v42, v48, v109
	v_exp_f32_e32 v62, v42
	v_sub_f32_e32 v42, v64, v109
	v_exp_f32_e32 v60, v42
	v_add_f32_e32 v63, v45, v121
	v_sub_f32_e32 v42, v49, v109
	v_cvt_pk_bf16_f32 v47, v34, v35
	v_add_f32_e32 v154, v62, v60
	v_add_f32_e32 v155, v63, v61
	v_exp_f32_e32 v61, v42
	v_sub_f32_e32 v42, v65, v109
	v_exp_f32_e32 v63, v42
	v_cvt_pk_bf16_f32 v42, v40, v41
	v_cvt_pk_bf16_f32 v40, v50, v51
	v_cvt_pk_bf16_f32 v41, v52, v53
	ds_read_b128 v[50:53], v163 offset:40960
	v_cvt_pk_bf16_f32 v48, v36, v37
	v_cvt_pk_bf16_f32 v49, v38, v39
	v_mul_f32_e32 v32, v32, v156
	v_mul_f32_e32 v33, v33, v156
	v_mul_f32_e32 v30, v30, v156
	v_mul_f32_e32 v31, v31, v156
	s_waitcnt lgkmcnt(0)
	v_mfma_f32_32x32x16_bf16 v[2:17], v[50:53], v[46:49], v[2:17]
	ds_read_b128 v[50:53], v163 offset:45056
	v_mul_f32_e64 v28, v28, v156
	v_mul_f32_e64 v29, v29, v156
	v_mul_f32_e64 v26, v26, v156
	v_mul_f32_e64 v27, v27, v156
	v_mul_f32_e32 v24, v24, v156
	v_mul_f32_e32 v25, v25, v156
	v_mul_f32_e32 v22, v22, v156
	v_mul_f32_e32 v23, v23, v156
	v_mul_f32_e32 v20, v20, v156
	v_mul_f32_e32 v21, v21, v156
	v_mul_f32_e32 v18, v18, v156
	v_mul_f32_e32 v19, v19, v156
	v_cvt_pk_bf16_f32 v43, v58, v57
	v_cvt_pk_bf16_f32 v44, v44, v45
	s_waitcnt lgkmcnt(0)
	v_mfma_f32_32x32x16_bf16 v[18:33], v[50:53], v[46:49], v[18:33]
	ds_read_b128 v[46:49], v162 offset:40960
	v_cvt_pk_bf16_f32 v45, v62, v61
	v_cvt_pk_bf16_f32 v38, v113, v117
	v_cvt_pk_bf16_f32 v39, v158, v119
	v_cvt_pk_bf16_f32 v34, v54, v55
	v_cvt_pk_bf16_f32 v35, v56, v59
	v_cvt_pk_bf16_f32 v36, v164, v121
	s_waitcnt lgkmcnt(0)
	v_mfma_f32_32x32x16_bf16 v[2:17], v[46:49], v[42:45], v[2:17]
	ds_read_b128 v[46:49], v162 offset:45056
	v_cvt_pk_bf16_f32 v37, v60, v63
	ds_read_b128 v[50:53], v103 offset:53248
	v_add_f32_e32 v152, v61, v63
	s_waitcnt lgkmcnt(1)
	v_mfma_f32_32x32x16_bf16 v[18:33], v[46:49], v[42:45], v[18:33]
	ds_read_b128 v[42:45], v161 offset:40960
	s_waitcnt lgkmcnt(0)
	v_mfma_f32_32x32x16_bf16 v[2:17], v[42:45], v[38:41], v[2:17]
	ds_read_b128 v[42:45], v161 offset:45056
	s_waitcnt lgkmcnt(0)
	v_mfma_f32_32x32x16_bf16 v[18:33], v[42:45], v[38:41], v[18:33]
	ds_read_b128 v[38:41], v160 offset:40960
	s_waitcnt lgkmcnt(0)
	v_mfma_f32_32x32x16_bf16 v[2:17], v[38:41], v[34:37], v[2:17]
	ds_read_b128 v[38:41], v160 offset:45056
	s_waitcnt lgkmcnt(0)
	v_mfma_f32_32x32x16_bf16 v[18:33], v[38:41], v[34:37], v[18:33]
	ds_read_b128 v[34:37], v103 offset:49152
	s_waitcnt lgkmcnt(0)
	v_mfma_f32_32x32x16_bf16 v[34:49], v[34:37], v[94:97], 0
	v_mfma_f32_32x32x16_bf16 v[50:65], v[50:53], v[94:97], 0
	ds_read_b128 v[94:97], v105 offset:49152
	s_waitcnt lgkmcnt(0)
	v_mfma_f32_32x32x16_bf16 v[34:49], v[94:97], v[90:93], v[34:49]
	ds_read_b128 v[94:97], v105 offset:53248
	s_waitcnt lgkmcnt(0)
	v_mfma_f32_32x32x16_bf16 v[50:65], v[94:97], v[90:93], v[50:65]
	ds_read_b128 v[90:93], v107 offset:49152
	s_waitcnt lgkmcnt(0)
	v_mfma_f32_32x32x16_bf16 v[34:49], v[90:93], v[86:89], v[34:49]
	ds_read_b128 v[90:93], v107 offset:53248
	s_waitcnt lgkmcnt(0)
	v_mfma_f32_32x32x16_bf16 v[50:65], v[90:93], v[86:89], v[50:65]
	ds_read_b128 v[86:89], v101 offset:49152
	s_waitcnt lgkmcnt(0)
	v_mfma_f32_32x32x16_bf16 v[34:49], v[86:89], v[82:85], v[34:49]
	ds_read_b128 v[86:89], v101 offset:53248
	s_waitcnt lgkmcnt(0)
	v_mfma_f32_32x32x16_bf16 v[50:65], v[86:89], v[82:85], v[50:65]
	s_nop 8
	v_max_f32_e32 v1, v35, v35
	v_max_f32_e32 v82, v34, v34
	v_max_f32_e32 v1, v82, v1
	v_max3_f32 v1, v1, v36, v37
	v_max3_f32 v1, v1, v38, v39
	v_max3_f32 v1, v1, v40, v41
	v_max3_f32 v1, v1, v42, v43
	v_max3_f32 v1, v1, v44, v45
	v_max3_f32 v1, v1, v46, v47
	v_max3_f32 v1, v1, v48, v49
	v_max3_f32 v1, v1, v50, v51
	v_max3_f32 v1, v1, v52, v53
	v_max3_f32 v1, v1, v54, v55
	v_max3_f32 v1, v1, v56, v57
	v_max3_f32 v1, v1, v58, v59
	v_max3_f32 v1, v1, v60, v61
	v_max3_f32 v1, v1, v62, v63
	v_max3_f32 v1, v1, v64, v65
	v_mov_b32_e32 v82, v1
	s_nop 1
	v_permlane32_swap_b32_e32 v1, v82
	v_max3_f32 v82, v109, v1, v82
	v_sub_f32_e32 v1, v34, v82
	v_exp_f32_e32 v105, v1
	v_sub_f32_e32 v1, v50, v82
	v_exp_f32_e32 v101, v1
	v_sub_f32_e32 v1, v35, v82
	v_sub_f32_e32 v83, v109, v82
	v_exp_f32_e32 v109, v1
	v_sub_f32_e32 v1, v51, v82
	v_exp_f32_e32 v103, v1
	v_sub_f32_e32 v1, v36, v82
	v_exp_f32_e32 v113, v1
	v_sub_f32_e32 v1, v52, v82
	v_exp_f32_e32 v107, v1
	v_sub_f32_e32 v1, v37, v82
	v_exp_f32_e32 v117, v1
	v_sub_f32_e32 v1, v53, v82
	v_exp_f32_e32 v111, v1
	v_sub_f32_e32 v1, v38, v82
	v_exp_f32_e32 v121, v1
	v_sub_f32_e32 v1, v54, v82
	v_exp_f32_e32 v115, v1
	v_sub_f32_e32 v1, v39, v82
	v_exp_f32_e32 v123, v1
	v_sub_f32_e32 v1, v55, v82
	v_exp_f32_e32 v119, v1
	v_sub_f32_e32 v1, v40, v82
	v_exp_f32_e32 v129, v1
	v_sub_f32_e32 v1, v56, v82
	v_exp_f32_e32 v125, v1
	v_sub_f32_e32 v1, v41, v82
	v_exp_f32_e32 v133, v1
	v_sub_f32_e32 v1, v57, v82
	v_exp_f32_e32 v127, v1
	v_sub_f32_e32 v1, v42, v82
	v_add_f32_e32 v34, v104, v100
	v_add_f32_e32 v35, v105, v101
	v_exp_f32_e32 v137, v1
	v_sub_f32_e32 v1, v58, v82
	v_add_f32_e32 v34, v34, v144
	v_add_f32_e32 v35, v35, v145
	v_add_f32_e32 v36, v108, v102
	v_add_f32_e32 v37, v109, v103
	v_exp_f32_e32 v131, v1
	v_sub_f32_e32 v1, v43, v82
	v_add_f32_e32 v34, v36, v34
	v_add_f32_e32 v35, v37, v35
	v_add_f32_e32 v36, v112, v106
	v_add_f32_e32 v37, v113, v107
	v_exp_f32_e32 v141, v1
	v_sub_f32_e32 v1, v59, v82
	v_add_f32_e32 v34, v36, v34
	v_add_f32_e32 v35, v37, v35
	v_add_f32_e32 v36, v116, v110
	v_add_f32_e32 v37, v117, v111
	v_exp_f32_e32 v135, v1
	v_sub_f32_e32 v1, v44, v82
	v_add_f32_e32 v34, v36, v34
	v_add_f32_e32 v35, v37, v35
	v_add_f32_e32 v36, v120, v114
	v_add_f32_e32 v37, v121, v115
	v_exp_f32_e32 v143, v1
	v_sub_f32_e32 v1, v60, v82
	v_exp_f32_e32 v139, v1
	v_sub_f32_e32 v1, v45, v82
	v_add_f32_e32 v34, v36, v34
	v_add_f32_e32 v35, v37, v35
	v_add_f32_e32 v36, v122, v118
	v_add_f32_e32 v37, v123, v119
	v_exp_f32_e32 v53, v1
	v_sub_f32_e32 v1, v61, v82
	v_sub_f32_e32 v38, v46, v82
	v_add_f32_e32 v34, v36, v34
	v_add_f32_e32 v35, v37, v35
	v_add_f32_e32 v36, v128, v124
	v_add_f32_e32 v37, v129, v125
	v_exp_f32_e32 v54, v1
	v_exp_f32_e32 v55, v38
	v_sub_f32_e32 v38, v62, v82
	v_add_f32_e32 v34, v36, v34
	v_add_f32_e32 v35, v37, v35
	v_add_f32_e32 v36, v132, v126
	v_add_f32_e32 v37, v133, v127
	v_exp_f32_e32 v56, v38
	v_add_f32_e32 v34, v36, v34
	v_add_f32_e32 v35, v37, v35
	v_add_f32_e32 v36, v136, v130
	v_add_f32_e32 v37, v137, v131
	v_sub_f32_e32 v38, v47, v82
	v_add_f32_e32 v34, v36, v34
	v_add_f32_e32 v35, v37, v35
	v_add_f32_e32 v36, v140, v134
	v_add_f32_e32 v37, v141, v135
	v_exp_f32_e32 v147, v38
	v_sub_f32_e32 v38, v63, v82
	v_add_f32_e32 v34, v36, v34
	v_add_f32_e32 v35, v37, v35
	v_add_f32_e32 v36, v142, v138
	v_add_f32_e32 v37, v143, v139
	v_add_f32_e32 v1, v53, v54
	v_exp_f32_e32 v57, v38
	v_sub_f32_e32 v38, v48, v82
	v_add_f32_e32 v34, v36, v34
	v_add_f32_e32 v35, v37, v35
	v_add_f32_e32 v151, v55, v56
	v_exp_f32_e32 v58, v38
	v_sub_f32_e32 v38, v64, v82
	v_add_f32_e32 v0, v0, v34
	v_add_f32_e32 v1, v1, v35
	v_exp_f32_e32 v59, v38
	v_mul_f32_e32 v34, v0, v150
	v_mul_f32_e32 v35, v1, v151
	v_add_f32_e32 v0, v0, v150
	v_add_f32_e32 v1, v1, v151
	v_sub_f32_e32 v38, v49, v82
	v_mov_b32_e32 v35, v1
	v_add_f32_e32 v0, v148, v149
	v_add_f32_e32 v1, v149, v148
	v_exp_f32_e32 v153, v38
	v_sub_f32_e32 v38, v65, v82
	v_mov_b32_e32 v1, v57
	v_exp_f32_e32 v60, v38
	v_add_f32_e32 v0, v146, v0
	v_add_f32_e32 v1, v147, v1
	v_add_f32_e32 v157, v58, v59
	v_add_f32_e32 v0, v34, v0
	v_add_f32_e32 v1, v35, v1
	v_exp_f32_e32 v52, v83
	v_mul_f32_e32 v34, v0, v156
	v_mul_f32_e32 v35, v1, v157
	v_add_f32_e32 v0, v0, v156
	v_add_f32_e32 v1, v1, v157
	v_mul_f32_e32 v48, v16, v52
	v_mul_f32_e32 v49, v17, v52
	v_mov_b32_e32 v35, v1
	v_add_f32_e32 v0, v154, v155
	v_add_f32_e32 v1, v155, v154
	v_mul_f32_e32 v40, v8, v52
	v_mul_f32_e32 v41, v9, v52
	v_mov_b32_e32 v1, v60
	v_add_f32_e32 v0, v152, v0
	v_add_f32_e32 v1, v153, v1
	v_mul_f32_e32 v8, v26, v52
	v_mul_f32_e32 v9, v27, v52
	v_add_f32_e32 v50, v34, v0
	v_add_f32_e32 v51, v35, v1
	v_mul_f32_e32 v0, v18, v52
	v_mul_f32_e32 v1, v19, v52
	v_cvt_pk_bf16_f32 v26, v55, v147
	v_cvt_pk_bf16_f32 v17, v139, v54
	v_cvt_pk_bf16_f32 v18, v56, v57
	ds_read_b128 v[54:57], v163 offset:57344
	v_mul_f32_e32 v46, v14, v52
	v_mul_f32_e32 v47, v15, v52
	v_mul_f32_e32 v44, v12, v52
	v_mul_f32_e32 v45, v13, v52
	v_mul_f32_e32 v42, v10, v52
	v_mul_f32_e32 v43, v11, v52
	v_mul_f32_e32 v38, v6, v52
	v_mul_f32_e32 v39, v7, v52
	v_mul_f32_e32 v36, v4, v52
	v_mul_f32_e32 v37, v5, v52
	v_mul_f32_e32 v34, v2, v52
	v_mul_f32_e32 v35, v3, v52
	v_mul_f32_e32 v12, v30, v52
	v_mul_f32_e32 v13, v31, v52
	v_mul_f32_e32 v10, v28, v52
	v_mul_f32_e32 v11, v29, v52
	v_cvt_pk_bf16_f32 v28, v105, v109
	v_cvt_pk_bf16_f32 v29, v113, v117
	v_cvt_pk_bf16_f32 v30, v121, v123
	v_cvt_pk_bf16_f32 v31, v129, v133
	v_mul_f32_e32 v14, v32, v52
	v_mul_f32_e32 v15, v33, v52
	v_mul_f32_e32 v6, v24, v52
	v_mul_f32_e32 v7, v25, v52
	s_waitcnt lgkmcnt(0)
	v_mfma_f32_32x32x16_bf16 v[34:49], v[54:57], v[28:31], v[34:49]
	ds_read_b128 v[54:57], v163 offset:61440
	v_mul_f32_e64 v4, v22, v52
	v_mul_f32_e64 v5, v23, v52
	v_mul_f32_e64 v2, v20, v52
	v_mul_f32_e64 v3, v21, v52
	v_cvt_pk_bf16_f32 v24, v137, v141
	v_cvt_pk_bf16_f32 v25, v143, v53
	v_cvt_pk_bf16_f32 v27, v58, v153
	v_cvt_pk_bf16_f32 v20, v101, v103
	s_waitcnt lgkmcnt(0)
	v_mfma_f32_32x32x16_bf16 v[0:15], v[54:57], v[28:31], v[0:15]
	ds_read_b128 v[28:31], v162 offset:57344
	v_cvt_pk_bf16_f32 v21, v107, v111
	v_cvt_pk_bf16_f32 v22, v115, v119
	v_cvt_pk_bf16_f32 v23, v125, v127
	v_cvt_pk_bf16_f32 v16, v131, v135
	v_cvt_pk_bf16_f32 v19, v59, v60
	v_fmac_f32_e32 v51, v50, v52
	s_waitcnt lgkmcnt(0)
	v_mfma_f32_32x32x16_bf16 v[34:49], v[28:31], v[24:27], v[34:49]
	ds_read_b128 v[28:31], v162 offset:61440
	s_waitcnt lgkmcnt(0)
	v_mfma_f32_32x32x16_bf16 v[0:15], v[28:31], v[24:27], v[0:15]
	ds_read_b128 v[24:27], v161 offset:57344
	s_waitcnt lgkmcnt(0)
	v_mfma_f32_32x32x16_bf16 v[34:49], v[24:27], v[20:23], v[34:49]
	ds_read_b128 v[24:27], v161 offset:61440
	s_waitcnt lgkmcnt(0)
	v_mfma_f32_32x32x16_bf16 v[0:15], v[24:27], v[20:23], v[0:15]
	ds_read_b128 v[20:23], v160 offset:57344
	s_waitcnt vmcnt(3)
	v_mov_b32_e32 v26, v81
	s_nop 1
	v_permlane32_swap_b32_e32 v79, v26
	s_waitcnt lgkmcnt(0)
	v_mfma_f32_32x32x16_bf16 v[34:49], v[20:23], v[16:19], v[34:49]
	ds_read_b128 v[20:23], v160 offset:61440
	s_waitcnt lgkmcnt(0)
	v_mfma_f32_32x32x16_bf16 v[0:15], v[20:23], v[16:19], v[0:15]
	v_mov_b32_e32 v16, v51
	s_nop 1
	v_permlane32_swap_b32_e32 v51, v16
	v_add_f32_e32 v16, v51, v16
	v_div_scale_f32 v17, s[2:3], v16, v16, 1.0
	v_rcp_f32_e32 v18, v17
	s_nop 0
	v_fma_f32 v19, -v17, v18, 1.0
	v_fmac_f32_e32 v18, v19, v18
	v_div_scale_f32 v19, vcc, 1.0, v16, 1.0
	v_mul_f32_e32 v20, v19, v18
	v_fma_f32 v21, -v17, v20, v19
	v_fmac_f32_e32 v20, v21, v18
	v_fma_f32 v17, -v17, v20, v19
	v_div_fmas_f32 v17, v17, v18, v20
	v_div_fixup_f32 v20, v17, v16, 1.0
	v_lshlrev_b64 v[16:17], 11, v[98:99]
	v_mov_b32_e32 v21, v80
	v_lshl_add_u64 v[16:17], s[0:1], 0, v[16:17]
	s_nop 0
	v_permlane32_swap_b32_e32 v78, v21
	v_lshl_add_u64 v[22:23], v[16:17], 0, v[176:177]
	v_lshlrev_b32_e32 v16, 16, v78
	v_and_b32_e32 v17, 0xffff0000, v78
	v_mul_f32_e32 v18, v34, v20
	v_mul_f32_e32 v19, v35, v20
	v_mul_f32_e32 v24, v36, v20
	v_mul_f32_e32 v25, v37, v20
	v_mul_f32_e32 v16, v18, v16
	v_mul_f32_e32 v17, v19, v17
	v_lshlrev_b32_e32 v18, 16, v79
	v_and_b32_e32 v19, 0xffff0000, v79
	v_mul_f32_e32 v18, v24, v18
	v_mul_f32_e32 v19, v25, v19
	v_cvt_pk_bf16_f32 v16, v16, v17
	v_cvt_pk_bf16_f32 v17, v18, v19
	v_lshlrev_b32_e32 v18, 16, v21
	v_and_b32_e32 v19, 0xffff0000, v21
	v_mul_f32_e32 v24, v38, v20
	v_mul_f32_e32 v25, v39, v20
	s_nop 0
	v_mul_f32_e32 v18, v24, v18
	v_mul_f32_e32 v19, v25, v19
	v_lshlrev_b32_e32 v24, 16, v26
	v_and_b32_e32 v25, 0xffff0000, v26
	v_mul_f32_e32 v26, v40, v20
	v_mul_f32_e32 v27, v41, v20
	v_cvt_pk_bf16_f32 v18, v18, v19
	v_mul_f32_e32 v24, v26, v24
	v_mul_f32_e32 v25, v27, v25
	s_waitcnt vmcnt(2)
	v_mov_b32_e32 v21, v76
	v_cvt_pk_bf16_f32 v19, v24, v25
	v_permlane32_swap_b32_e32 v16, v18
	s_nop 0
	v_permlane32_swap_b32_e32 v17, v19
	v_permlane32_swap_b32_e32 v74, v21
	v_mov_b32_e32 v26, v77
	global_store_dwordx4 v[22:23], v[16:19], off offset:1536
	s_nop 0
	v_permlane32_swap_b32_e32 v75, v26
	v_lshlrev_b32_e32 v16, 16, v74
	v_and_b32_e32 v17, 0xffff0000, v74
	v_mul_f32_e32 v18, v42, v20
	v_mul_f32_e32 v19, v43, v20
	v_mul_f32_e32 v24, v44, v20
	v_mul_f32_e32 v25, v45, v20
	v_mul_f32_e32 v16, v18, v16
	v_mul_f32_e32 v17, v19, v17
	v_lshlrev_b32_e32 v18, 16, v75
	v_and_b32_e32 v19, 0xffff0000, v75
	v_mul_f32_e32 v18, v24, v18
	v_mul_f32_e32 v19, v25, v19
	v_cvt_pk_bf16_f32 v16, v16, v17
	v_cvt_pk_bf16_f32 v17, v18, v19
	v_lshlrev_b32_e32 v18, 16, v21
	v_and_b32_e32 v19, 0xffff0000, v21
	v_mul_f32_e32 v24, v46, v20
	v_mul_f32_e32 v25, v47, v20
	v_mul_f32_e32 v0, v0, v20
	v_mul_f32_e32 v1, v1, v20
	v_mul_f32_e32 v18, v24, v18
	v_mul_f32_e32 v19, v25, v19
	v_lshlrev_b32_e32 v24, 16, v26
	v_and_b32_e32 v25, 0xffff0000, v26
	v_mul_f32_e32 v26, v48, v20
	v_mul_f32_e32 v27, v49, v20
	v_cvt_pk_bf16_f32 v18, v18, v19
	v_mul_f32_e32 v24, v26, v24
	v_mul_f32_e32 v25, v27, v25
	s_nop 0
	v_permlane32_swap_b32_e32 v16, v18
	v_cvt_pk_bf16_f32 v19, v24, v25
	s_nop 1
	v_permlane32_swap_b32_e32 v17, v19
	global_store_dwordx4 v[22:23], v[16:19], off offset:1568
	v_mul_f32_e32 v2, v2, v20
	v_mul_f32_e32 v3, v3, v20
	v_mul_f32_e32 v4, v4, v20
	v_mul_f32_e32 v5, v5, v20
	s_waitcnt vmcnt(3)
	v_mov_b32_e32 v18, v72
	s_nop 1
	v_permlane32_swap_b32_e32 v70, v18
	v_mov_b32_e32 v19, v73
	s_nop 1
	v_permlane32_swap_b32_e32 v71, v19
	v_lshlrev_b32_e32 v16, 16, v70
	v_and_b32_e32 v17, 0xffff0000, v70
	v_mul_f32_e32 v0, v0, v16
	v_mul_f32_e32 v1, v1, v17
	v_lshlrev_b32_e32 v16, 16, v71
	v_and_b32_e32 v17, 0xffff0000, v71
	v_mul_f32_e32 v2, v2, v16
	v_mul_f32_e32 v3, v3, v17
	v_cvt_pk_bf16_f32 v0, v0, v1
	v_cvt_pk_bf16_f32 v1, v2, v3
	v_lshlrev_b32_e32 v2, 16, v18
	v_and_b32_e32 v3, 0xffff0000, v18
	v_mul_f32_e32 v2, v4, v2
	v_mul_f32_e32 v3, v5, v3
	v_lshlrev_b32_e32 v4, 16, v19
	v_and_b32_e32 v5, 0xffff0000, v19
	v_mul_f32_e32 v6, v6, v20
	v_mul_f32_e32 v7, v7, v20
	v_cvt_pk_bf16_f32 v2, v2, v3
	v_mul_f32_e32 v4, v6, v4
	v_mul_f32_e32 v5, v7, v5
	s_waitcnt vmcnt(2)
	v_mov_b32_e32 v6, v68
	v_cvt_pk_bf16_f32 v3, v4, v5
	v_permlane32_swap_b32_e32 v0, v2
	s_nop 0
	v_permlane32_swap_b32_e32 v1, v3
	v_permlane32_swap_b32_e32 v66, v6
	v_mov_b32_e32 v7, v69
	global_store_dwordx4 v[22:23], v[0:3], off offset:1600
	s_nop 0
	v_permlane32_swap_b32_e32 v67, v7
	v_lshlrev_b32_e32 v0, 16, v66
	v_and_b32_e32 v1, 0xffff0000, v66
	v_mul_f32_e32 v2, v8, v20
	v_mul_f32_e32 v3, v9, v20
	v_mul_f32_e32 v4, v10, v20
	v_mul_f32_e32 v5, v11, v20
	v_mul_f32_e32 v0, v2, v0
	v_mul_f32_e32 v1, v3, v1
	v_lshlrev_b32_e32 v2, 16, v67
	v_and_b32_e32 v3, 0xffff0000, v67
	v_mul_f32_e32 v2, v4, v2
	v_mul_f32_e32 v3, v5, v3
	v_cvt_pk_bf16_f32 v0, v0, v1
	v_cvt_pk_bf16_f32 v1, v2, v3
	v_lshlrev_b32_e32 v2, 16, v6
	v_and_b32_e32 v3, 0xffff0000, v6
	v_mul_f32_e32 v4, v12, v20
	v_mul_f32_e32 v5, v13, v20
	s_nop 0
	v_mul_f32_e32 v2, v4, v2
	v_mul_f32_e32 v3, v5, v3
	v_lshlrev_b32_e32 v4, 16, v7
	v_and_b32_e32 v5, 0xffff0000, v7
	v_mul_f32_e32 v6, v14, v20
	v_mul_f32_e32 v7, v15, v20
	v_cvt_pk_bf16_f32 v2, v2, v3
	v_mul_f32_e32 v4, v6, v4
	v_mul_f32_e32 v5, v7, v5
	s_nop 0
	v_permlane32_swap_b32_e32 v0, v2
	v_cvt_pk_bf16_f32 v3, v4, v5
	s_nop 1
	v_permlane32_swap_b32_e32 v1, v3
	global_store_dwordx4 v[22:23], v[0:3], off offset:1632
	s_cbranch_scc1 .LBB0_907

.LBB0_918:
	s_or_b64 exec, exec, s[2:3]
	s_movk_i32 s0, 0x100
	v_cmp_gt_u32_e64 s[0:1], s0, v126
	v_mov_b32_e32 v112, 0x180
	v_and_b32_e32 v132, 15, v126
	v_cndmask_b32_e64 v182, v231, v112, s[0:1]
	v_lshrrev_b32_e32 v112, 2, v126
	v_and_b32_e32 v133, 48, v112
	v_mov_b32_e32 v112, 0x80
	v_readlane_b32 s8, v253, 18
	v_cndmask_b32_e32 v184, 0, v112, vcc
	v_mov_b64_e32 v[112:113], s[92:93]
	v_or3_b32 v114, s8, v132, v133
	v_mad_i64_i32 v[112:113], s[0:1], v114, s33, v[112:113]
	v_and_b32_e32 v128, 48, v126
	v_mov_b32_e32 v129, v177
	v_mov_b32_e32 v183, v177
	v_mov_b32_e32 v185, v177
	v_lshl_add_u64 v[130:131], v[112:113], 0, v[128:129]
	v_lshl_add_u64 v[120:121], v[130:131], 0, v[182:183]
	v_lshl_add_u64 v[130:131], v[130:131], 0, v[184:185]
	global_load_dwordx4 v[112:115], v[120:121], off offset:576
	s_nop 0
	global_load_dwordx4 v[120:123], v[120:121], off offset:512
	s_nop 0
	global_load_dwordx4 v[140:143], v[130:131], off offset:576
	global_load_dwordx4 v[144:147], v[130:131], off offset:512
	v_lshlrev_b32_e32 v127, 3, v127
	s_movk_i32 s0, 0xff
	v_or_b32_e32 v188, v133, v132
	v_lshlrev_b32_e32 v130, 6, v125
	v_cmp_lt_u32_e64 s[36:37], s0, v126
	v_lshlrev_b32_e32 v126, 1, v127
	v_mov_b32_e32 v127, v177
	v_mul_u32_u24_e32 v243, 0x210, v188
	v_lshlrev_b32_e32 v125, 7, v125
	s_movk_i32 s0, 0x210
	v_lshl_add_u64 v[186:187], s[94:95], 0, v[126:127]
	v_add3_u32 v244, v243, v125, v178
	v_mul_lo_u32 v125, v179, s0
	v_mul_lo_u32 v126, v239, s0
	v_mul_lo_u32 v127, v240, s0
	v_mul_lo_u32 v131, v241, s0
	v_mul_lo_u32 v132, v242, s0
	v_add_u32_e32 v245, 0x12d0, v244
	v_add_u32_e32 v246, 0x14e0, v244
	v_add_u32_e32 v247, 0x16f0, v244
	v_add_u32_e32 v248, 0x1b10, v244
	v_add_u32_e32 v249, 0x1d20, v244
	v_add_u32_e32 v233, 0x1f30, v244
	v_lshl_add_u64 v[190:191], s[92:93], 0, v[128:129]
	v_add_u32_e32 v251, v176, v125
	v_add_u32_e32 v252, v176, v126
	v_add_u32_e32 v238, v176, v127
	v_add_u32_e32 v231, v176, v131
	v_add_u32_e32 v232, v176, v132
	v_lshlrev_b32_e32 v176, 1, v124
	v_lshlrev_b32_e32 v192, 1, v130
	s_mov_b32 s6, s46
	s_waitcnt vmcnt(0)
	s_branch .LBB0_920

.LBB0_920:
	s_add_i32 s9, s6, s90
	s_cmpk_gt_i32 s9, 0x2ff
	s_cselect_b64 s[0:1], -1, 0
	s_cmpk_lt_i32 s9, 0x300
	s_cselect_b32 s2, s9, s6
	s_lshl_b32 s7, s2, 6
	s_cmpk_lt_i32 s2, 0x200
	s_cselect_b32 s11, s89, 0x1000
	s_add_i32 s2, s11, -1
	s_and_b32 s12, s2, s7
	s_waitcnt lgkmcnt(0)
	s_barrier
	s_add_i32 s12, s12, -8
	s_waitcnt vmcnt(8)
	ds_write_b128 v251, v[96:99]
	ds_write_b128 v252, v[100:103]
	ds_write_b128 v238, v[104:107]
	ds_write_b128 v231, v[108:111]
	ds_write_b128 v232, v[116:119]
	v_add_u32_e32 v96, s12, v179
	s_add_i32 s10, s7, -8
	v_cmp_gt_u32_e32 vcc, s11, v96
	v_mov_b32_e32 v100, 0
	v_mov_b32_e32 v96, 0
	v_mov_b32_e32 v97, 0
	v_mov_b32_e32 v98, 0
	v_mov_b32_e32 v99, 0
	s_and_saveexec_b64 s[2:3], vcc
	s_cbranch_execz .LBB0_922
	v_add_u32_e32 v96, s10, v179
	v_mad_i64_i32 v[96:97], s[14:15], v96, s33, v[180:181]
	global_load_dwordx4 v[96:99], v[96:97], off
